# residual epilogues (P4, P8) round 1: counted vmcnt waits per 16-row group instead of one vmcnt(0)
# baseline (speedup 1.0000x reference)
.LBB5_539:
	v_lshl_or_b32 v192, s10, 8, v206
	v_lshl_add_u32 v196, s38, 8, v204
	v_ashrrev_i32_e32 v193, 31, v192
	v_ashrrev_i32_e32 v197, 31, v196
	v_lshl_add_u64 v[194:195], v[192:193], 2, s[36:37]
	v_lshlrev_b64 v[128:129], 12, v[196:197]
	v_lshl_add_u64 v[128:129], v[194:195], 0, v[128:129]
	global_load_dwordx4 v[212:215], v[128:129], off
	global_load_dwordx4 v[216:219], v[128:129], off offset:16
	global_load_dwordx4 v[220:223], v[128:129], off offset:512
	global_load_dwordx4 v[224:227], v[128:129], off offset:528
	v_or_b32_e32 v202, 16, v196
	v_or_b32_e32 v200, 32, v196
	v_or_b32_e32 v198, 48, v196
	v_ashrrev_i32_e32 v203, 31, v202
	v_ashrrev_i32_e32 v201, 31, v200
	v_ashrrev_i32_e32 v199, 31, v198
	v_lshlrev_b64 v[128:129], 12, v[202:203]
	v_lshlrev_b64 v[130:131], 12, v[200:201]
	v_lshlrev_b64 v[132:133], 12, v[198:199]
	v_lshl_add_u64 v[128:129], v[194:195], 0, v[128:129]
	v_lshl_add_u64 v[130:131], v[194:195], 0, v[130:131]
	v_lshl_add_u64 v[132:133], v[194:195], 0, v[132:133]
	global_load_dwordx4 v[168:171], v[128:129], off offset:16
	global_load_dwordx4 v[172:175], v[128:129], off
	global_load_dwordx4 v[160:163], v[128:129], off offset:528
	global_load_dwordx4 v[164:167], v[128:129], off offset:512
	global_load_dwordx4 v[152:155], v[130:131], off offset:16
	global_load_dwordx4 v[156:159], v[130:131], off
	global_load_dwordx4 v[144:147], v[130:131], off offset:528
	global_load_dwordx4 v[148:151], v[130:131], off offset:512
	global_load_dwordx4 v[136:139], v[132:133], off offset:16
	global_load_dwordx4 v[140:143], v[132:133], off
	s_nop 0
	global_load_dwordx4 v[128:131], v[132:133], off offset:528
	s_nop 0
	global_load_dwordx4 v[132:135], v[132:133], off offset:512
	v_lshlrev_b64 v[228:229], 11, v[196:197]
	s_lshl_b32 s38, s10, 2
	s_ashr_i32 s39, s38, 31
	s_waitcnt vmcnt(12)
	v_pk_add_f32 v[126:127], v[126:127], v[214:215]
	v_pk_add_f32 v[124:125], v[124:125], v[212:213]
	v_pk_add_f32 v[118:119], v[118:119], v[222:223]
	v_pk_add_f32 v[116:117], v[116:117], v[220:221]
	v_pk_add_f32 v[122:123], v[122:123], v[218:219]
	v_pk_add_f32 v[120:121], v[120:121], v[216:217]
	v_pk_add_f32 v[214:215], v[112:113], v[224:225]
	v_cvt_pk_bf16_f32 v112, v124, v125
	v_cvt_pk_bf16_f32 v113, v126, v127
	v_mul_f32_e32 v125, v125, v125
	v_mul_f32_e32 v127, v127, v127
	v_mul_f32_e32 v216, v117, v117
	v_mul_f32_e32 v217, v119, v119
	v_pk_add_f32 v[212:213], v[114:115], v[226:227]
	v_cvt_pk_bf16_f32 v114, v120, v121
	v_cvt_pk_bf16_f32 v115, v122, v123
	v_mul_f32_e32 v121, v121, v121
	v_mul_f32_e32 v123, v123, v123
	v_mul_f32_e32 v218, v215, v215
	v_fmac_f32_e32 v125, v124, v124
	v_fmac_f32_e32 v127, v126, v126
	v_fmac_f32_e32 v216, v116, v116
	v_fmac_f32_e32 v217, v118, v118
	v_mul_f32_e32 v219, v213, v213
	v_fmac_f32_e32 v121, v120, v120
	v_fmac_f32_e32 v123, v122, v122
	v_fmac_f32_e32 v218, v214, v214
	v_add_f32_e32 v120, v125, v127
	v_add_f32_e32 v122, v216, v217
	v_fmac_f32_e32 v219, v212, v212
	v_add_f32_e32 v120, v120, v121
	v_add_f32_e32 v121, v122, v218
	v_add_f32_e32 v120, v123, v120
	v_add_f32_e32 v121, v219, v121
	v_add_f32_e32 v122, v120, v121
	ds_bpermute_b32 v123, v207, v122
	v_lshl_add_u64 v[120:121], s[70:71], 0, v[228:229]
	v_lshl_add_u64 v[120:121], v[192:193], 1, v[120:121]
	global_store_dwordx4 v[120:121], v[112:115], off
	s_waitcnt lgkmcnt(0)
	s_nop 0
	v_add_f32_e32 v112, v122, v123
	ds_bpermute_b32 v113, v208, v112
	v_cvt_pk_bf16_f32 v114, v116, v117
	v_cvt_pk_bf16_f32 v115, v118, v119
	v_cvt_pk_bf16_f32 v116, v214, v215
	v_cvt_pk_bf16_f32 v117, v212, v213
	global_store_dwordx4 v[120:121], v[114:117], off offset:256
	s_and_saveexec_b64 s[40:41], s[0:1]
	s_cbranch_execz .LBB5_541
	v_lshlrev_b64 v[114:115], 6, v[196:197]
	v_lshl_add_u64 v[114:115], s[12:13], 0, v[114:115]
	v_lshl_add_u64 v[114:115], s[38:39], 2, v[114:115]
	s_lshl_b32 s10, s46, 2
	v_lshl_add_u64 v[114:115], v[114:115], 0, s[10:11]
	s_waitcnt lgkmcnt(0)
	v_add_f32_e32 v112, v112, v113
	global_store_dword v[114:115], v112, off
.LBB5_541:
	s_waitcnt vmcnt(10)
	s_nop 0
	s_nop 0
	s_nop 0
	s_nop 0
	s_nop 0
	s_nop 0
	s_nop 0
	s_nop 0
	s_nop 0
	s_nop 0
	s_nop 0
	s_nop 0
	s_nop 0
	s_or_b64 exec, exec, s[40:41]
	v_pk_add_f32 v[108:109], v[108:109], v[172:173]
	v_pk_add_f32 v[110:111], v[110:111], v[174:175]
	v_pk_add_f32 v[116:117], v[104:105], v[168:169]
	v_cvt_pk_bf16_f32 v104, v108, v109
	v_mul_f32_e32 v109, v109, v109
	v_fmac_f32_e32 v109, v108, v108
	v_mul_f32_e32 v108, v111, v111
	v_fmac_f32_e32 v108, v110, v110
	v_add_f32_e32 v108, v109, v108
	v_mul_f32_e32 v109, v117, v117
	v_pk_add_f32 v[102:103], v[102:103], v[166:167]
	v_pk_add_f32 v[100:101], v[100:101], v[164:165]
	v_pk_add_f32 v[114:115], v[106:107], v[170:171]
	v_cvt_pk_bf16_f32 v105, v110, v111
	v_fmac_f32_e32 v109, v116, v116
	v_pk_add_f32 v[110:111], v[96:97], v[160:161]
	v_mul_f32_e32 v96, v101, v101
	v_mul_f32_e32 v97, v103, v103
	v_add_f32_e32 v108, v108, v109
	v_mul_f32_e32 v109, v115, v115
	v_fmac_f32_e32 v96, v100, v100
	v_fmac_f32_e32 v97, v102, v102
	v_fmac_f32_e32 v109, v114, v114
	v_add_f32_e32 v96, v96, v97
	v_mul_f32_e32 v97, v111, v111
	v_cvt_pk_bf16_f32 v106, v116, v117
	v_cvt_pk_bf16_f32 v107, v114, v115
	v_add_f32_e32 v114, v109, v108
	v_pk_add_f32 v[108:109], v[98:99], v[162:163]
	v_fmac_f32_e32 v97, v110, v110
	v_add_f32_e32 v96, v96, v97
	v_mul_f32_e32 v97, v109, v109
	v_fmac_f32_e32 v97, v108, v108
	v_add_f32_e32 v96, v97, v96
	v_add_f32_e32 v99, v114, v96
	ds_bpermute_b32 v114, v207, v99
	s_waitcnt lgkmcnt(1)
	v_lshlrev_b64 v[112:113], 11, v[202:203]
	v_lshl_add_u64 v[96:97], s[70:71], 0, v[112:113]
	v_lshl_add_u64 v[112:113], v[192:193], 1, v[96:97]
	global_store_dwordx4 v[112:113], v[104:107], off
	s_waitcnt lgkmcnt(0)
	v_add_f32_e32 v96, v99, v114
	ds_bpermute_b32 v97, v208, v96
	v_cvt_pk_bf16_f32 v98, v100, v101
	v_cvt_pk_bf16_f32 v99, v102, v103
	v_cvt_pk_bf16_f32 v100, v110, v111
	v_cvt_pk_bf16_f32 v101, v108, v109
	global_store_dwordx4 v[112:113], v[98:101], off offset:256
	s_and_saveexec_b64 s[40:41], s[0:1]
	s_cbranch_execz .LBB5_543
	v_lshlrev_b64 v[98:99], 6, v[202:203]
	v_lshl_add_u64 v[98:99], s[12:13], 0, v[98:99]
	v_lshl_add_u64 v[98:99], s[38:39], 2, v[98:99]
	s_lshl_b32 s10, s46, 2
	v_lshl_add_u64 v[98:99], v[98:99], 0, s[10:11]
	s_waitcnt lgkmcnt(0)
	v_add_f32_e32 v96, v96, v97
	global_store_dword v[98:99], v96, off
.LBB5_543:
	s_waitcnt vmcnt(8)
	s_or_b64 exec, exec, s[40:41]
	v_pk_add_f32 v[92:93], v[92:93], v[156:157]
	v_pk_add_f32 v[94:95], v[94:95], v[158:159]
	v_pk_add_f32 v[100:101], v[88:89], v[152:153]
	v_cvt_pk_bf16_f32 v88, v92, v93
	v_mul_f32_e32 v93, v93, v93
	v_fmac_f32_e32 v93, v92, v92
	v_mul_f32_e32 v92, v95, v95
	v_fmac_f32_e32 v92, v94, v94
	v_add_f32_e32 v92, v93, v92
	v_mul_f32_e32 v93, v101, v101
	v_pk_add_f32 v[86:87], v[86:87], v[150:151]
	v_pk_add_f32 v[84:85], v[84:85], v[148:149]
	v_pk_add_f32 v[98:99], v[90:91], v[154:155]
	v_cvt_pk_bf16_f32 v89, v94, v95
	v_fmac_f32_e32 v93, v100, v100
	v_pk_add_f32 v[94:95], v[80:81], v[144:145]
	v_mul_f32_e32 v80, v85, v85
	v_mul_f32_e32 v81, v87, v87
	v_add_f32_e32 v92, v92, v93
	v_mul_f32_e32 v93, v99, v99
	v_fmac_f32_e32 v80, v84, v84
	v_fmac_f32_e32 v81, v86, v86
	v_fmac_f32_e32 v93, v98, v98
	v_add_f32_e32 v80, v80, v81
	v_mul_f32_e32 v81, v95, v95
	v_cvt_pk_bf16_f32 v90, v100, v101
	v_cvt_pk_bf16_f32 v91, v98, v99
	v_add_f32_e32 v98, v93, v92
	v_pk_add_f32 v[92:93], v[82:83], v[146:147]
	v_fmac_f32_e32 v81, v94, v94
	v_add_f32_e32 v80, v80, v81
	v_mul_f32_e32 v81, v93, v93
	v_fmac_f32_e32 v81, v92, v92
	v_add_f32_e32 v80, v81, v80
	v_add_f32_e32 v83, v98, v80
	ds_bpermute_b32 v98, v207, v83
	s_waitcnt lgkmcnt(1)
	v_lshlrev_b64 v[96:97], 11, v[200:201]
	v_lshl_add_u64 v[80:81], s[70:71], 0, v[96:97]
	v_lshl_add_u64 v[96:97], v[192:193], 1, v[80:81]
	global_store_dwordx4 v[96:97], v[88:91], off
	s_waitcnt lgkmcnt(0)
	v_add_f32_e32 v80, v83, v98
	ds_bpermute_b32 v81, v208, v80
	v_cvt_pk_bf16_f32 v82, v84, v85
	v_cvt_pk_bf16_f32 v83, v86, v87
	v_cvt_pk_bf16_f32 v84, v94, v95
	v_cvt_pk_bf16_f32 v85, v92, v93
	global_store_dwordx4 v[96:97], v[82:85], off offset:256
	s_and_saveexec_b64 s[40:41], s[0:1]
	s_cbranch_execz .LBB5_545
	v_lshlrev_b64 v[82:83], 6, v[200:201]
	v_lshl_add_u64 v[82:83], s[12:13], 0, v[82:83]
	v_lshl_add_u64 v[82:83], s[38:39], 2, v[82:83]
	s_lshl_b32 s10, s46, 2
	v_lshl_add_u64 v[82:83], v[82:83], 0, s[10:11]
	s_waitcnt lgkmcnt(0)
	v_add_f32_e32 v80, v80, v81
	global_store_dword v[82:83], v80, off
.LBB5_545:
	s_waitcnt vmcnt(6)
	s_or_b64 exec, exec, s[40:41]
	v_pk_add_f32 v[76:77], v[76:77], v[140:141]
	v_pk_add_f32 v[78:79], v[78:79], v[142:143]
	v_pk_add_f32 v[84:85], v[72:73], v[136:137]
	v_cvt_pk_bf16_f32 v72, v76, v77
	v_mul_f32_e32 v77, v77, v77
	v_fmac_f32_e32 v77, v76, v76
	v_mul_f32_e32 v76, v79, v79
	v_fmac_f32_e32 v76, v78, v78
	v_add_f32_e32 v76, v77, v76
	v_mul_f32_e32 v77, v85, v85
	v_pk_add_f32 v[70:71], v[70:71], v[134:135]
	v_pk_add_f32 v[68:69], v[68:69], v[132:133]
	v_pk_add_f32 v[82:83], v[74:75], v[138:139]
	v_cvt_pk_bf16_f32 v73, v78, v79
	v_fmac_f32_e32 v77, v84, v84
	v_pk_add_f32 v[78:79], v[64:65], v[128:129]
	v_mul_f32_e32 v64, v69, v69
	v_mul_f32_e32 v65, v71, v71
	v_add_f32_e32 v76, v76, v77
	v_mul_f32_e32 v77, v83, v83
	v_fmac_f32_e32 v64, v68, v68
	v_fmac_f32_e32 v65, v70, v70
	v_fmac_f32_e32 v77, v82, v82
	v_add_f32_e32 v64, v64, v65
	v_mul_f32_e32 v65, v79, v79
	v_cvt_pk_bf16_f32 v74, v84, v85
	v_cvt_pk_bf16_f32 v75, v82, v83
	v_add_f32_e32 v82, v77, v76
	v_pk_add_f32 v[76:77], v[66:67], v[130:131]
	v_fmac_f32_e32 v65, v78, v78
	v_add_f32_e32 v64, v64, v65
	v_mul_f32_e32 v65, v77, v77
	v_fmac_f32_e32 v65, v76, v76
	v_add_f32_e32 v64, v65, v64
	v_add_f32_e32 v67, v82, v64
	ds_bpermute_b32 v82, v207, v67
	s_waitcnt lgkmcnt(1)
	v_lshlrev_b64 v[80:81], 11, v[198:199]
	v_lshl_add_u64 v[64:65], s[70:71], 0, v[80:81]
	v_lshl_add_u64 v[80:81], v[192:193], 1, v[64:65]
	global_store_dwordx4 v[80:81], v[72:75], off
	s_waitcnt lgkmcnt(0)
	v_add_f32_e32 v64, v67, v82
	ds_bpermute_b32 v65, v208, v64
	v_cvt_pk_bf16_f32 v66, v68, v69
	v_cvt_pk_bf16_f32 v67, v70, v71
	v_cvt_pk_bf16_f32 v68, v78, v79
	v_cvt_pk_bf16_f32 v69, v76, v77
	global_store_dwordx4 v[80:81], v[66:69], off offset:256
	s_and_saveexec_b64 s[40:41], s[0:1]
	s_cbranch_execz .LBB5_547
	v_lshlrev_b64 v[66:67], 6, v[198:199]
	v_lshl_add_u64 v[66:67], s[12:13], 0, v[66:67]
	v_lshl_add_u64 v[66:67], s[38:39], 2, v[66:67]
	s_lshl_b32 s10, s46, 2
	v_lshl_add_u64 v[66:67], v[66:67], 0, s[10:11]
	s_waitcnt lgkmcnt(0)
	v_add_f32_e32 v64, v64, v65
	global_store_dword v[66:67], v64, off

.LBB5_972:
	v_lshl_or_b32 v168, s10, 8, v188
	v_lshl_add_u32 v172, s36, 8, v186
	v_ashrrev_i32_e32 v169, 31, v168
	v_lshlrev_b64 v[202:203], 1, v[168:169]
	v_ashrrev_i32_e32 v173, 31, v172
	v_lshl_add_u64 v[170:171], s[70:71], 0, v[202:203]
	v_lshlrev_b64 v[204:205], 11, v[172:173]
	v_lshl_add_u64 v[128:129], v[170:171], 0, v[204:205]
	global_load_dwordx4 v[194:197], v[128:129], off
	global_load_dwordx4 v[198:201], v[128:129], off offset:256
	v_or_b32_e32 v182, 16, v172
	v_or_b32_e32 v178, 32, v172
	v_or_b32_e32 v174, 48, v172
	v_ashrrev_i32_e32 v183, 31, v182
	v_ashrrev_i32_e32 v179, 31, v178
	v_ashrrev_i32_e32 v175, 31, v174
	v_lshlrev_b64 v[184:185], 11, v[182:183]
	v_lshlrev_b64 v[180:181], 11, v[178:179]
	v_lshlrev_b64 v[176:177], 11, v[174:175]
	v_lshl_add_u64 v[128:129], v[170:171], 0, v[184:185]
	v_lshl_add_u64 v[130:131], v[170:171], 0, v[180:181]
	v_lshl_add_u64 v[206:207], v[170:171], 0, v[176:177]
	global_load_dwordx4 v[148:151], v[128:129], off
	global_load_dwordx4 v[144:147], v[128:129], off offset:256
	global_load_dwordx4 v[140:143], v[130:131], off
	global_load_dwordx4 v[136:139], v[130:131], off offset:256
	global_load_dwordx4 v[132:135], v[206:207], off
	s_nop 0
	global_load_dwordx4 v[128:131], v[206:207], off offset:256
	s_lshl_b32 s36, s10, 2
	s_ashr_i32 s37, s36, 31
	s_waitcnt vmcnt(6)
	v_lshlrev_b32_e32 v206, 16, v194
	v_and_b32_e32 v207, 0xffff0000, v194
	v_lshlrev_b32_e32 v194, 16, v195
	v_and_b32_e32 v195, 0xffff0000, v195
	v_lshlrev_b32_e32 v210, 16, v198
	v_and_b32_e32 v211, 0xffff0000, v198
	v_lshlrev_b32_e32 v198, 16, v199
	v_and_b32_e32 v199, 0xffff0000, v199
	v_lshlrev_b32_e32 v208, 16, v196
	v_and_b32_e32 v209, 0xffff0000, v196
	v_lshlrev_b32_e32 v196, 16, v197
	v_and_b32_e32 v197, 0xffff0000, v197
	v_lshlrev_b32_e32 v212, 16, v200
	v_and_b32_e32 v213, 0xffff0000, v200
	v_pk_add_f32 v[126:127], v[126:127], v[194:195]
	v_pk_add_f32 v[124:125], v[124:125], v[206:207]
	v_pk_add_f32 v[118:119], v[118:119], v[198:199]
	v_pk_add_f32 v[116:117], v[116:117], v[210:211]
	v_lshlrev_b32_e32 v200, 16, v201
	v_and_b32_e32 v201, 0xffff0000, v201
	v_pk_add_f32 v[122:123], v[122:123], v[196:197]
	v_pk_add_f32 v[120:121], v[120:121], v[208:209]
	v_pk_add_f32 v[196:197], v[112:113], v[212:213]
	v_cvt_pk_bf16_f32 v112, v124, v125
	v_cvt_pk_bf16_f32 v113, v126, v127
	v_mul_f32_e32 v125, v125, v125
	v_mul_f32_e32 v127, v127, v127
	v_mul_f32_e32 v198, v117, v117
	v_mul_f32_e32 v199, v119, v119
	v_pk_add_f32 v[194:195], v[114:115], v[200:201]
	v_cvt_pk_bf16_f32 v114, v120, v121
	v_cvt_pk_bf16_f32 v115, v122, v123
	v_mul_f32_e32 v121, v121, v121
	v_mul_f32_e32 v123, v123, v123
	v_mul_f32_e32 v200, v197, v197
	v_fmac_f32_e32 v125, v124, v124
	v_fmac_f32_e32 v127, v126, v126
	v_fmac_f32_e32 v198, v116, v116
	v_fmac_f32_e32 v199, v118, v118
	v_mul_f32_e32 v201, v195, v195
	v_fmac_f32_e32 v121, v120, v120
	v_fmac_f32_e32 v123, v122, v122
	v_fmac_f32_e32 v200, v196, v196
	v_add_f32_e32 v120, v125, v127
	v_add_f32_e32 v122, v198, v199
	v_fmac_f32_e32 v201, v194, v194
	v_add_f32_e32 v120, v121, v120
	v_add_f32_e32 v121, v200, v122
	v_add_f32_e32 v120, v123, v120
	v_add_f32_e32 v121, v201, v121
	v_add_f32_e32 v122, v120, v121
	ds_bpermute_b32 v123, v189, v122
	v_lshl_add_u64 v[120:121], s[12:13], 0, v[204:205]
	v_lshl_add_u64 v[120:121], v[120:121], 0, v[202:203]
	global_store_dwordx4 v[120:121], v[112:115], off
	s_waitcnt lgkmcnt(0)
	s_nop 0
	v_add_f32_e32 v112, v122, v123
	ds_bpermute_b32 v113, v190, v112
	v_cvt_pk_bf16_f32 v114, v116, v117
	v_cvt_pk_bf16_f32 v115, v118, v119
	v_cvt_pk_bf16_f32 v116, v196, v197
	v_cvt_pk_bf16_f32 v117, v194, v195
	global_store_dwordx4 v[120:121], v[114:117], off offset:256
	s_and_saveexec_b64 s[38:39], s[0:1]
	s_cbranch_execz .LBB5_974
	v_lshlrev_b64 v[114:115], 6, v[172:173]
	v_lshl_add_u64 v[114:115], s[14:15], 0, v[114:115]
	v_lshl_add_u64 v[114:115], s[36:37], 2, v[114:115]
	s_lshl_b32 s10, s46, 2
	v_lshl_add_u64 v[114:115], v[114:115], 0, s[10:11]
	s_waitcnt lgkmcnt(0)
	v_add_f32_e32 v112, v112, v113
	global_store_dword v[114:115], v112, off
.LBB5_974:
	s_waitcnt vmcnt(6)
	s_nop 0
	s_nop 0
	s_nop 0
	s_nop 0
	s_nop 0
	s_nop 0
	s_nop 0
	s_nop 0
	s_nop 0
	s_nop 0
	s_nop 0
	s_nop 0
	s_nop 0
	s_or_b64 exec, exec, s[38:39]
	v_lshlrev_b32_e32 v112, 16, v148
	s_waitcnt lgkmcnt(0)
	v_and_b32_e32 v113, 0xffff0000, v148
	v_lshlrev_b32_e32 v114, 16, v149
	v_and_b32_e32 v115, 0xffff0000, v149
	v_lshlrev_b32_e32 v116, 16, v150
	v_and_b32_e32 v117, 0xffff0000, v150
	v_pk_add_f32 v[108:109], v[108:109], v[112:113]
	v_pk_add_f32 v[110:111], v[110:111], v[114:115]
	v_pk_add_f32 v[114:115], v[104:105], v[116:117]
	v_cvt_pk_bf16_f32 v104, v108, v109
	v_mul_f32_e32 v109, v109, v109
	v_fmac_f32_e32 v109, v108, v108
	v_mul_f32_e32 v108, v111, v111
	v_lshlrev_b32_e32 v120, 16, v144
	v_and_b32_e32 v121, 0xffff0000, v144
	v_lshlrev_b32_e32 v122, 16, v145
	v_and_b32_e32 v123, 0xffff0000, v145
	v_fmac_f32_e32 v108, v110, v110
	v_lshlrev_b32_e32 v118, 16, v151
	v_and_b32_e32 v119, 0xffff0000, v151
	v_lshlrev_b32_e32 v124, 16, v146
	v_and_b32_e32 v125, 0xffff0000, v146
	v_add_f32_e32 v108, v109, v108
	v_mul_f32_e32 v109, v115, v115
	v_pk_add_f32 v[102:103], v[102:103], v[122:123]
	v_pk_add_f32 v[100:101], v[100:101], v[120:121]
	v_pk_add_f32 v[112:113], v[106:107], v[118:119]
	v_cvt_pk_bf16_f32 v105, v110, v111
	v_fmac_f32_e32 v109, v114, v114
	v_pk_add_f32 v[110:111], v[96:97], v[124:125]
	v_mul_f32_e32 v96, v101, v101
	v_mul_f32_e32 v97, v103, v103
	v_add_f32_e32 v108, v109, v108
	v_mul_f32_e32 v109, v113, v113
	v_fmac_f32_e32 v96, v100, v100
	v_fmac_f32_e32 v97, v102, v102
	v_lshlrev_b32_e32 v126, 16, v147
	v_and_b32_e32 v127, 0xffff0000, v147
	v_fmac_f32_e32 v109, v112, v112
	v_add_f32_e32 v96, v96, v97
	v_mul_f32_e32 v97, v111, v111
	v_cvt_pk_bf16_f32 v106, v114, v115
	v_cvt_pk_bf16_f32 v107, v112, v113
	v_add_f32_e32 v112, v109, v108
	v_pk_add_f32 v[108:109], v[98:99], v[126:127]
	v_fmac_f32_e32 v97, v110, v110
	v_add_f32_e32 v96, v97, v96
	v_mul_f32_e32 v97, v109, v109
	v_fmac_f32_e32 v97, v108, v108
	v_add_f32_e32 v96, v97, v96
	v_add_f32_e32 v99, v112, v96
	ds_bpermute_b32 v114, v189, v99
	v_lshl_add_u64 v[96:97], s[12:13], 0, v[184:185]
	v_lshl_add_u64 v[112:113], v[168:169], 1, v[96:97]
	global_store_dwordx4 v[112:113], v[104:107], off
	v_cvt_pk_bf16_f32 v98, v100, v101
	s_waitcnt lgkmcnt(0)
	v_add_f32_e32 v96, v99, v114
	ds_bpermute_b32 v97, v190, v96
	v_cvt_pk_bf16_f32 v99, v102, v103
	v_cvt_pk_bf16_f32 v100, v110, v111
	v_cvt_pk_bf16_f32 v101, v108, v109
	global_store_dwordx4 v[112:113], v[98:101], off offset:256
	s_and_saveexec_b64 s[38:39], s[0:1]
	s_cbranch_execz .LBB5_976
	v_lshlrev_b64 v[98:99], 6, v[182:183]
	v_lshl_add_u64 v[98:99], s[14:15], 0, v[98:99]
	v_lshl_add_u64 v[98:99], s[36:37], 2, v[98:99]
	s_lshl_b32 s10, s46, 2
	v_lshl_add_u64 v[98:99], v[98:99], 0, s[10:11]
	s_waitcnt lgkmcnt(0)
	v_add_f32_e32 v96, v96, v97
	global_store_dword v[98:99], v96, off
.LBB5_976:
	s_waitcnt vmcnt(6)
	s_or_b64 exec, exec, s[38:39]
	v_lshlrev_b32_e32 v96, 16, v140
	s_waitcnt lgkmcnt(0)
	v_and_b32_e32 v97, 0xffff0000, v140
	v_lshlrev_b32_e32 v98, 16, v141
	v_and_b32_e32 v99, 0xffff0000, v141
	v_lshlrev_b32_e32 v100, 16, v142
	v_and_b32_e32 v101, 0xffff0000, v142
	v_pk_add_f32 v[92:93], v[92:93], v[96:97]
	v_pk_add_f32 v[94:95], v[94:95], v[98:99]
	v_pk_add_f32 v[98:99], v[88:89], v[100:101]
	v_cvt_pk_bf16_f32 v88, v92, v93
	v_mul_f32_e32 v93, v93, v93
	v_fmac_f32_e32 v93, v92, v92
	v_mul_f32_e32 v92, v95, v95
	v_lshlrev_b32_e32 v104, 16, v136
	v_and_b32_e32 v105, 0xffff0000, v136
	v_lshlrev_b32_e32 v106, 16, v137
	v_and_b32_e32 v107, 0xffff0000, v137
	v_fmac_f32_e32 v92, v94, v94
	v_lshlrev_b32_e32 v102, 16, v143
	v_and_b32_e32 v103, 0xffff0000, v143
	v_lshlrev_b32_e32 v108, 16, v138
	v_and_b32_e32 v109, 0xffff0000, v138
	v_add_f32_e32 v92, v93, v92
	v_mul_f32_e32 v93, v99, v99
	v_pk_add_f32 v[86:87], v[86:87], v[106:107]
	v_pk_add_f32 v[84:85], v[84:85], v[104:105]
	v_pk_add_f32 v[96:97], v[90:91], v[102:103]
	v_cvt_pk_bf16_f32 v89, v94, v95
	v_fmac_f32_e32 v93, v98, v98
	v_pk_add_f32 v[94:95], v[80:81], v[108:109]
	v_mul_f32_e32 v80, v85, v85
	v_mul_f32_e32 v81, v87, v87
	v_add_f32_e32 v92, v93, v92
	v_mul_f32_e32 v93, v97, v97
	v_fmac_f32_e32 v80, v84, v84
	v_fmac_f32_e32 v81, v86, v86
	v_lshlrev_b32_e32 v110, 16, v139
	v_and_b32_e32 v111, 0xffff0000, v139
	v_fmac_f32_e32 v93, v96, v96
	v_add_f32_e32 v80, v80, v81
	v_mul_f32_e32 v81, v95, v95
	v_cvt_pk_bf16_f32 v90, v98, v99
	v_cvt_pk_bf16_f32 v91, v96, v97
	v_add_f32_e32 v96, v93, v92
	v_pk_add_f32 v[92:93], v[82:83], v[110:111]
	v_fmac_f32_e32 v81, v94, v94
	v_add_f32_e32 v80, v81, v80
	v_mul_f32_e32 v81, v93, v93
	v_fmac_f32_e32 v81, v92, v92
	v_add_f32_e32 v80, v81, v80
	v_add_f32_e32 v83, v96, v80
	ds_bpermute_b32 v98, v189, v83
	v_lshl_add_u64 v[80:81], s[12:13], 0, v[180:181]
	v_lshl_add_u64 v[96:97], v[168:169], 1, v[80:81]
	global_store_dwordx4 v[96:97], v[88:91], off
	v_cvt_pk_bf16_f32 v82, v84, v85
	s_waitcnt lgkmcnt(0)
	v_add_f32_e32 v80, v83, v98
	ds_bpermute_b32 v81, v190, v80
	v_cvt_pk_bf16_f32 v83, v86, v87
	v_cvt_pk_bf16_f32 v84, v94, v95
	v_cvt_pk_bf16_f32 v85, v92, v93
	global_store_dwordx4 v[96:97], v[82:85], off offset:256
	s_and_saveexec_b64 s[38:39], s[0:1]
	s_cbranch_execz .LBB5_978
	v_lshlrev_b64 v[82:83], 6, v[178:179]
	v_lshl_add_u64 v[82:83], s[14:15], 0, v[82:83]
	v_lshl_add_u64 v[82:83], s[36:37], 2, v[82:83]
	s_lshl_b32 s10, s46, 2
	v_lshl_add_u64 v[82:83], v[82:83], 0, s[10:11]
	s_waitcnt lgkmcnt(0)
	v_add_f32_e32 v80, v80, v81
	global_store_dword v[82:83], v80, off
.LBB5_978:
	s_waitcnt vmcnt(6)
	s_or_b64 exec, exec, s[38:39]
	v_lshlrev_b32_e32 v80, 16, v132
	s_waitcnt lgkmcnt(0)
	v_and_b32_e32 v81, 0xffff0000, v132
	v_lshlrev_b32_e32 v82, 16, v133
	v_and_b32_e32 v83, 0xffff0000, v133
	v_lshlrev_b32_e32 v84, 16, v134
	v_and_b32_e32 v85, 0xffff0000, v134
	v_pk_add_f32 v[76:77], v[76:77], v[80:81]
	v_pk_add_f32 v[78:79], v[78:79], v[82:83]
	v_pk_add_f32 v[82:83], v[72:73], v[84:85]
	v_cvt_pk_bf16_f32 v72, v76, v77
	v_mul_f32_e32 v77, v77, v77
	v_fmac_f32_e32 v77, v76, v76
	v_mul_f32_e32 v76, v79, v79
	v_lshlrev_b32_e32 v88, 16, v128
	v_and_b32_e32 v89, 0xffff0000, v128
	v_lshlrev_b32_e32 v90, 16, v129
	v_and_b32_e32 v91, 0xffff0000, v129
	v_fmac_f32_e32 v76, v78, v78
	v_lshlrev_b32_e32 v86, 16, v135
	v_and_b32_e32 v87, 0xffff0000, v135
	v_lshlrev_b32_e32 v92, 16, v130
	v_and_b32_e32 v93, 0xffff0000, v130
	v_add_f32_e32 v76, v77, v76
	v_mul_f32_e32 v77, v83, v83
	v_pk_add_f32 v[70:71], v[70:71], v[90:91]
	v_pk_add_f32 v[68:69], v[68:69], v[88:89]
	v_pk_add_f32 v[80:81], v[74:75], v[86:87]
	v_cvt_pk_bf16_f32 v73, v78, v79
	v_fmac_f32_e32 v77, v82, v82
	v_pk_add_f32 v[78:79], v[64:65], v[92:93]
	v_mul_f32_e32 v64, v69, v69
	v_mul_f32_e32 v65, v71, v71
	v_add_f32_e32 v76, v77, v76
	v_mul_f32_e32 v77, v81, v81
	v_fmac_f32_e32 v64, v68, v68
	v_fmac_f32_e32 v65, v70, v70
	v_lshlrev_b32_e32 v94, 16, v131
	v_and_b32_e32 v95, 0xffff0000, v131
	v_fmac_f32_e32 v77, v80, v80
	v_add_f32_e32 v64, v64, v65
	v_mul_f32_e32 v65, v79, v79
	v_cvt_pk_bf16_f32 v74, v82, v83
	v_cvt_pk_bf16_f32 v75, v80, v81
	v_add_f32_e32 v80, v77, v76
	v_pk_add_f32 v[76:77], v[66:67], v[94:95]
	v_fmac_f32_e32 v65, v78, v78
	v_add_f32_e32 v64, v65, v64
	v_mul_f32_e32 v65, v77, v77
	v_fmac_f32_e32 v65, v76, v76
	v_add_f32_e32 v64, v65, v64
	v_add_f32_e32 v67, v80, v64
	ds_bpermute_b32 v82, v189, v67
	v_lshl_add_u64 v[64:65], s[12:13], 0, v[176:177]
	v_lshl_add_u64 v[80:81], v[168:169], 1, v[64:65]
	global_store_dwordx4 v[80:81], v[72:75], off
	v_cvt_pk_bf16_f32 v66, v68, v69
	s_waitcnt lgkmcnt(0)
	v_add_f32_e32 v64, v67, v82
	ds_bpermute_b32 v65, v190, v64
	v_cvt_pk_bf16_f32 v67, v70, v71
	v_cvt_pk_bf16_f32 v68, v78, v79
	v_cvt_pk_bf16_f32 v69, v76, v77
	global_store_dwordx4 v[80:81], v[66:69], off offset:256
	s_and_saveexec_b64 s[38:39], s[0:1]
	s_cbranch_execz .LBB5_980
	v_lshlrev_b64 v[66:67], 6, v[174:175]
	v_lshl_add_u64 v[66:67], s[14:15], 0, v[66:67]
	v_lshl_add_u64 v[66:67], s[36:37], 2, v[66:67]
	s_lshl_b32 s10, s46, 2
	v_lshl_add_u64 v[66:67], v[66:67], 0, s[10:11]
	s_waitcnt lgkmcnt(0)
	v_add_f32_e32 v64, v64, v65
	global_store_dword v[66:67], v64, off
